# down-proj GEMM epilogue de-serialised: residual loads issued in batches of 8 before one wait instead of a load-wait-store ladder (on top of A-attention DMA edit)
# baseline (speedup 1.0000x reference)
; DI unsigned pk2(float lo, float hi) { f32x2 v = {lo, hi}; bf16x2_t b = __builtin_convertvector(v, bf16x2_t); return __builtin_bit_cast(unsigned, b); }
;   DI void operator()(ACC_T, const Unit& u, int wr, int wc, int fr, int fq) const {
; #pragma unroll
;     for (int ai = 0; ai < 2; ++ai)
; #pragma unroll
;       for (int m = 0; m < 4; ++m) {
;         const int row = EROW(u, ai, m);
;         const size_t ro = (size_t)row * DM + u.pn * 256 + wc * 32 + 4 * fq;
;         float ss = 0.f;
; #pragma unroll
;         for (int bj = 0; bj < 2; ++bj)
; #pragma unroll
;           for (int n = 0; n < 2; ++n) {
;             const size_t o = ro + bj * 128 + n * 16; const f32x4 x = *(const f32x4*)(xs + o) + acc[ai][bj][m][n]; *(f32x4*)(xd + o) = x;
;             if (NORM_OUT) { u32x2 w; w.x = pk2(x[0], x[1]); w.y = pk2(x[2], x[3]); *(u32x2*)(xb + o) = w; ss += x[0] * x[0] + x[1] * x[1] + x[2] * x[2] + x[3] * x[3]; }
;           }
;         if (NORM_OUT) { ss += __shfl_xor(ss, 16); ss += __shfl_xor(ss, 32); if (fq == 0) __hip_atomic_fetch_add(ssq + row, ss, __ATOMIC_RELAXED, __HIP_MEMORY_SCOPE_AGENT); }
;       }
;   }
.LBB0_987:
	v_lshl_add_u32 v138, s51, 8, v131
	s_lshl_b32 s9, s50, 8
	s_ashr_i32 s11, s9, 31
	v_ashrrev_i32_e32 v139, 31, v138
	v_mov_b32_e32 v137, s11
	v_or_b32_e32 v136, s9, v130
	v_lshlrev_b64 v[142:143], 12, v[138:139]
	v_lshl_add_u64 v[142:143], s[4:5], 0, v[142:143]
	v_lshlrev_b64 v[136:137], 2, v[136:137]
	v_lshl_add_u64 v[146:147], v[142:143], 0, v[136:137]
	s_mov_b64 s[16:17], -1
	s_andn2_b64 vcc, exec, s[40:41]
	v_add_u32_e32 v142, 0x10, v138
	v_ashrrev_i32_e32 v143, 31, v142
	v_lshlrev_b64 v[142:143], 12, v[142:143]
	v_lshl_add_u64 v[142:143], s[4:5], 0, v[142:143]
	v_lshl_add_u64 v[142:143], v[142:143], 0, v[136:137]
	global_load_dwordx4 v[152:155], v[146:147], off
	global_load_dwordx4 v[156:159], v[146:147], off offset:64
	global_load_dwordx4 v[160:163], v[146:147], off offset:512
	global_load_dwordx4 v[180:183], v[146:147], off offset:576
	global_load_dwordx4 v[184:187], v[142:143], off
	global_load_dwordx4 v[188:191], v[142:143], off offset:64
	global_load_dwordx4 v[192:195], v[142:143], off offset:512
	global_load_dwordx4 v[200:203], v[142:143], off offset:576
	s_waitcnt vmcnt(0)
	v_pk_add_f32 v[126:127], v[126:127], v[154:155]
	v_pk_add_f32 v[124:125], v[124:125], v[152:153]
	global_store_dwordx4 v[146:147], v[124:127], off
	v_pk_add_f32 v[122:123], v[122:123], v[158:159]
	v_pk_add_f32 v[120:121], v[120:121], v[156:157]
	global_store_dwordx4 v[146:147], v[120:123], off offset:64
	v_pk_add_f32 v[118:119], v[118:119], v[162:163]
	v_pk_add_f32 v[116:117], v[116:117], v[160:161]
	global_store_dwordx4 v[146:147], v[116:119], off offset:512
	v_pk_add_f32 v[114:115], v[114:115], v[182:183]
	v_pk_add_f32 v[112:113], v[112:113], v[180:181]
	global_store_dwordx4 v[146:147], v[112:115], off offset:576
	v_pk_add_f32 v[110:111], v[110:111], v[186:187]
	v_pk_add_f32 v[108:109], v[108:109], v[184:185]
	global_store_dwordx4 v[142:143], v[108:111], off
	v_pk_add_f32 v[106:107], v[106:107], v[190:191]
	v_pk_add_f32 v[104:105], v[104:105], v[188:189]
	global_store_dwordx4 v[142:143], v[104:107], off offset:64
	v_pk_add_f32 v[102:103], v[102:103], v[194:195]
	v_pk_add_f32 v[100:101], v[100:101], v[192:193]
	global_store_dwordx4 v[142:143], v[100:103], off offset:512
	v_pk_add_f32 v[98:99], v[98:99], v[202:203]
	v_pk_add_f32 v[96:97], v[96:97], v[200:201]
	global_store_dwordx4 v[142:143], v[96:99], off offset:576
	v_add_u32_e32 v146, 0x20, v138
	v_ashrrev_i32_e32 v147, 31, v146
	v_lshlrev_b64 v[146:147], 12, v[146:147]
	v_lshl_add_u64 v[146:147], s[4:5], 0, v[146:147]
	v_lshl_add_u64 v[146:147], v[146:147], 0, v[136:137]
	v_add_u32_e32 v142, 0x30, v138
	v_ashrrev_i32_e32 v143, 31, v142
	v_lshlrev_b64 v[142:143], 12, v[142:143]
	v_lshl_add_u64 v[142:143], s[4:5], 0, v[142:143]
	v_lshl_add_u64 v[142:143], v[142:143], 0, v[136:137]
	global_load_dwordx4 v[152:155], v[146:147], off
	global_load_dwordx4 v[156:159], v[146:147], off offset:64
	global_load_dwordx4 v[160:163], v[146:147], off offset:512
	global_load_dwordx4 v[180:183], v[146:147], off offset:576
	global_load_dwordx4 v[184:187], v[142:143], off
	global_load_dwordx4 v[188:191], v[142:143], off offset:64
	global_load_dwordx4 v[192:195], v[142:143], off offset:512
	global_load_dwordx4 v[200:203], v[142:143], off offset:576
	s_waitcnt vmcnt(0)
	v_pk_add_f32 v[94:95], v[94:95], v[154:155]
	v_pk_add_f32 v[92:93], v[92:93], v[152:153]
	global_store_dwordx4 v[146:147], v[92:95], off
	v_pk_add_f32 v[90:91], v[90:91], v[158:159]
	v_pk_add_f32 v[88:89], v[88:89], v[156:157]
	global_store_dwordx4 v[146:147], v[88:91], off offset:64
	v_pk_add_f32 v[86:87], v[86:87], v[162:163]
	v_pk_add_f32 v[84:85], v[84:85], v[160:161]
	global_store_dwordx4 v[146:147], v[84:87], off offset:512
	v_pk_add_f32 v[82:83], v[82:83], v[182:183]
	v_pk_add_f32 v[80:81], v[80:81], v[180:181]
	global_store_dwordx4 v[146:147], v[80:83], off offset:576
	v_pk_add_f32 v[78:79], v[78:79], v[186:187]
	v_pk_add_f32 v[76:77], v[76:77], v[184:185]
	global_store_dwordx4 v[142:143], v[76:79], off
	v_pk_add_f32 v[74:75], v[74:75], v[190:191]
	v_pk_add_f32 v[72:73], v[72:73], v[188:189]
	global_store_dwordx4 v[142:143], v[72:75], off offset:64
	v_pk_add_f32 v[70:71], v[70:71], v[194:195]
	v_pk_add_f32 v[68:69], v[68:69], v[192:193]
	global_store_dwordx4 v[142:143], v[68:71], off offset:512
	v_pk_add_f32 v[66:67], v[66:67], v[202:203]
	v_pk_add_f32 v[64:65], v[64:65], v[200:201]
	global_store_dwordx4 v[142:143], v[64:67], off offset:576
	v_add_u32_e32 v146, 0x80, v138
	v_ashrrev_i32_e32 v147, 31, v146
	v_lshlrev_b64 v[146:147], 12, v[146:147]
	v_lshl_add_u64 v[146:147], s[4:5], 0, v[146:147]
	v_lshl_add_u64 v[146:147], v[146:147], 0, v[136:137]
	v_add_u32_e32 v142, 0x90, v138
	v_ashrrev_i32_e32 v143, 31, v142
	v_lshlrev_b64 v[142:143], 12, v[142:143]
	v_lshl_add_u64 v[142:143], s[4:5], 0, v[142:143]
	v_lshl_add_u64 v[142:143], v[142:143], 0, v[136:137]
	global_load_dwordx4 v[152:155], v[146:147], off
	global_load_dwordx4 v[156:159], v[146:147], off offset:64
	global_load_dwordx4 v[160:163], v[146:147], off offset:512
	global_load_dwordx4 v[180:183], v[146:147], off offset:576
	global_load_dwordx4 v[184:187], v[142:143], off
	global_load_dwordx4 v[188:191], v[142:143], off offset:64
	global_load_dwordx4 v[192:195], v[142:143], off offset:512
	global_load_dwordx4 v[200:203], v[142:143], off offset:576
	s_waitcnt vmcnt(0)
; DI unsigned pk2(float lo, float hi) { f32x2 v = {lo, hi}; bf16x2_t b = __builtin_convertvector(v, bf16x2_t); return __builtin_bit_cast(unsigned, b); }
;   DI void operator()(ACC_T, const Unit& u, int wr, int wc, int fr, int fq) const {
; #pragma unroll
;     for (int ai = 0; ai < 2; ++ai)
; #pragma unroll
;       for (int m = 0; m < 4; ++m) {
;         const int row = EROW(u, ai, m);
;         const size_t ro = (size_t)row * DM + u.pn * 256 + wc * 32 + 4 * fq;
;         float ss = 0.f;
; #pragma unroll
;         for (int bj = 0; bj < 2; ++bj)
; #pragma unroll
;           for (int n = 0; n < 2; ++n) {
;             const size_t o = ro + bj * 128 + n * 16; const f32x4 x = *(const f32x4*)(xs + o) + acc[ai][bj][m][n]; *(f32x4*)(xd + o) = x;
;             if (NORM_OUT) { u32x2 w; w.x = pk2(x[0], x[1]); w.y = pk2(x[2], x[3]); *(u32x2*)(xb + o) = w; ss += x[0] * x[0] + x[1] * x[1] + x[2] * x[2] + x[3] * x[3]; }
;           }
;         if (NORM_OUT) { ss += __shfl_xor(ss, 16); ss += __shfl_xor(ss, 32); if (fq == 0) __hip_atomic_fetch_add(ssq + row, ss, __ATOMIC_RELAXED, __HIP_MEMORY_SCOPE_AGENT); }
;       }
;   }
	v_pk_add_f32 v[62:63], v[62:63], v[154:155]
	v_pk_add_f32 v[60:61], v[60:61], v[152:153]
	global_store_dwordx4 v[146:147], v[60:63], off
	v_pk_add_f32 v[58:59], v[58:59], v[158:159]
	v_pk_add_f32 v[56:57], v[56:57], v[156:157]
	global_store_dwordx4 v[146:147], v[56:59], off offset:64
	v_pk_add_f32 v[54:55], v[54:55], v[162:163]
	v_pk_add_f32 v[52:53], v[52:53], v[160:161]
	global_store_dwordx4 v[146:147], v[52:55], off offset:512
	v_pk_add_f32 v[50:51], v[50:51], v[182:183]
	v_pk_add_f32 v[48:49], v[48:49], v[180:181]
	global_store_dwordx4 v[146:147], v[48:51], off offset:576
	v_pk_add_f32 v[46:47], v[46:47], v[186:187]
	v_pk_add_f32 v[44:45], v[44:45], v[184:185]
	global_store_dwordx4 v[142:143], v[44:47], off
	v_pk_add_f32 v[42:43], v[42:43], v[190:191]
	v_pk_add_f32 v[40:41], v[40:41], v[188:189]
	global_store_dwordx4 v[142:143], v[40:43], off offset:64
	v_pk_add_f32 v[38:39], v[38:39], v[194:195]
	v_pk_add_f32 v[36:37], v[36:37], v[192:193]
	global_store_dwordx4 v[142:143], v[36:39], off offset:512
	v_pk_add_f32 v[34:35], v[34:35], v[202:203]
	v_pk_add_f32 v[32:33], v[32:33], v[200:201]
	global_store_dwordx4 v[142:143], v[32:35], off offset:576
	v_add_u32_e32 v146, 0xa0, v138
	v_ashrrev_i32_e32 v147, 31, v146
	v_lshlrev_b64 v[146:147], 12, v[146:147]
	v_lshl_add_u64 v[146:147], s[4:5], 0, v[146:147]
	v_lshl_add_u64 v[146:147], v[146:147], 0, v[136:137]
	v_add_u32_e32 v142, 0xb0, v138
	v_ashrrev_i32_e32 v143, 31, v142
	v_lshlrev_b64 v[142:143], 12, v[142:143]
	v_lshl_add_u64 v[142:143], s[4:5], 0, v[142:143]
	v_lshl_add_u64 v[142:143], v[142:143], 0, v[136:137]
	global_load_dwordx4 v[152:155], v[146:147], off
	global_load_dwordx4 v[156:159], v[146:147], off offset:64
	global_load_dwordx4 v[160:163], v[146:147], off offset:512
	global_load_dwordx4 v[180:183], v[146:147], off offset:576
	global_load_dwordx4 v[184:187], v[142:143], off
	global_load_dwordx4 v[188:191], v[142:143], off offset:64
	global_load_dwordx4 v[192:195], v[142:143], off offset:512
	global_load_dwordx4 v[200:203], v[142:143], off offset:576
	s_waitcnt vmcnt(0)
	v_pk_add_f32 v[30:31], v[30:31], v[154:155]
	v_pk_add_f32 v[28:29], v[28:29], v[152:153]
	global_store_dwordx4 v[146:147], v[28:31], off
	v_pk_add_f32 v[26:27], v[26:27], v[158:159]
	v_pk_add_f32 v[24:25], v[24:25], v[156:157]
	global_store_dwordx4 v[146:147], v[24:27], off offset:64
	v_pk_add_f32 v[22:23], v[22:23], v[162:163]
	v_pk_add_f32 v[20:21], v[20:21], v[160:161]
	global_store_dwordx4 v[146:147], v[20:23], off offset:512
	v_pk_add_f32 v[18:19], v[18:19], v[182:183]
	v_pk_add_f32 v[16:17], v[16:17], v[180:181]
	global_store_dwordx4 v[146:147], v[16:19], off offset:576
	v_pk_add_f32 v[14:15], v[14:15], v[186:187]
	v_pk_add_f32 v[12:13], v[12:13], v[184:185]
	global_store_dwordx4 v[142:143], v[12:15], off
	v_pk_add_f32 v[10:11], v[10:11], v[190:191]
	v_pk_add_f32 v[8:9], v[8:9], v[188:189]
	global_store_dwordx4 v[142:143], v[8:11], off offset:64
	v_pk_add_f32 v[6:7], v[6:7], v[194:195]
	v_pk_add_f32 v[4:5], v[4:5], v[192:193]
	global_store_dwordx4 v[142:143], v[4:7], off offset:512
	v_pk_add_f32 v[2:3], v[2:3], v[202:203]
	v_pk_add_f32 v[0:1], v[0:1], v[200:201]
	global_store_dwordx4 v[142:143], v[0:3], off offset:576
	s_cbranch_vccnz .LBB0_976
	s_andn2_b64 vcc, exec, s[0:1]
	s_cbranch_vccnz .LBB0_975
	s_barrier
	s_branch .LBB0_975
